# P11 conv+gelu: waits moved so next 4 rows prefetch stays in flight during the current group (vmcnt(0) only on the rare state-load path)
# baseline (speedup 1.0000x reference)
.LBB0_1778:
	s_waitcnt vmcnt(1)
	v_mov_b64_e32 v[100:101], v[44:45]
	v_mov_b64_e32 v[92:93], v[52:53]
	v_mov_b64_e32 v[84:85], v[60:61]
	v_mov_b64_e32 v[34:35], v[66:67]
	v_mov_b64_e32 v[112:113], v[40:41]
	v_mov_b64_e32 v[96:97], v[48:49]
	v_mov_b64_e32 v[88:89], v[56:57]
	v_mov_b64_e32 v[72:73], v[64:65]
	v_lshl_add_u64 v[142:143], v[142:143], 0, s[24:25]
	s_cmp_ge_i32 s75, s38
	v_mov_b64_e32 v[98:99], v[42:43]
	v_mov_b64_e32 v[90:91], v[50:51]
	v_mov_b64_e32 v[82:83], v[58:59]
	v_mov_b64_e32 v[36:37], v[68:69]
	v_mov_b64_e32 v[110:111], v[38:39]
	v_mov_b64_e32 v[94:95], v[46:47]
	v_mov_b64_e32 v[86:87], v[54:55]
	v_mov_b64_e32 v[70:71], v[62:63]
	s_mov_b32 s76, s75
	s_cbranch_scc1 .LBB0_1770
.LBB0_1779:
	s_add_i32 s75, s76, 4
	s_min_i32 s4, s75, s39
	v_mad_i64_i32 v[38:39], s[4:5], s4, v144, v[136:137]
	s_add_i32 s4, s76, 5
	s_min_i32 s4, s4, s39
	v_mad_i64_i32 v[46:47], s[4:5], s4, v144, v[136:137]
	v_add_co_u32_e32 v42, vcc, s41, v38
	s_add_i32 s4, s76, 6
	s_nop 0
	v_addc_co_u32_e32 v43, vcc, 0, v39, vcc
	s_min_i32 s4, s4, s39
	v_add_co_u32_e32 v50, vcc, s41, v46
	v_mad_i64_i32 v[54:55], s[4:5], s4, v144, v[136:137]
	s_nop 0
	v_addc_co_u32_e32 v51, vcc, 0, v47, vcc
	s_add_i32 s4, s76, 7
	v_add_co_u32_e32 v58, vcc, s41, v54
	s_min_i32 s4, s4, s39
	s_nop 0
	v_addc_co_u32_e32 v59, vcc, 0, v55, vcc
	v_mad_i64_i32 v[62:63], s[4:5], s4, v144, v[136:137]
	v_add_co_u32_e32 v66, vcc, s41, v62
	global_load_dwordx4 v[38:41], v[38:39], off
	s_nop 0
	global_load_dwordx4 v[42:45], v[42:43], off offset:1536
	v_addc_co_u32_e32 v67, vcc, 0, v63, vcc
	global_load_dwordx4 v[46:49], v[46:47], off
	s_nop 0
	global_load_dwordx4 v[50:53], v[50:51], off offset:1536
	s_nop 0
	global_load_dwordx4 v[54:57], v[54:55], off
	s_nop 0
	global_load_dwordx4 v[58:61], v[58:59], off offset:1536
	s_nop 0
	global_load_dwordx4 v[62:65], v[62:63], off
	s_nop 0
	global_load_dwordx4 v[66:69], v[66:67], off offset:1536
	s_add_i32 s4, s76, 0xffffe000
	s_lshr_b32 s16, s4, 3
	s_ashr_i32 s36, s76, 11
	s_cmpk_lt_i32 s76, 0x2000
	s_cselect_b64 s[72:73], -1, 0
	s_and_b64 s[4:5], s[72:73], exec
	s_cselect_b32 s4, 0x7ff, 7
	s_cselect_b32 s78, s36, s16
	s_and_b32 s77, s4, s76
	s_cmp_lg_u32 s77, 0
	s_cselect_b64 s[4:5], -1, 0
	s_or_b64 s[80:81], s[4:5], s[72:73]
	s_andn2_b64 vcc, exec, s[80:81]
	v_mad_i64_i32 v[118:119], s[80:81], s78, v145, v[140:141]
	s_cbranch_vccz .LBB0_1781
	v_add_co_u32_e32 v116, vcc, 0xa000, v118
	v_lshl_add_u64 v[114:115], v[118:119], 0, s[18:19]
	s_nop 0
	v_addc_co_u32_e32 v117, vcc, 0, v119, vcc
	global_load_dwordx4 v[122:125], v[116:117], off offset:3072
	s_nop 0
	global_load_dwordx4 v[114:117], v[114:115], off offset:16
	s_waitcnt vmcnt(0)
	s_branch .LBB0_1782

.LBB0_1782:
	s_cmp_gt_u32 s77, 1
	s_cselect_b64 s[4:5], -1, 0
	s_or_b64 s[80:81], s[4:5], s[72:73]
	s_and_b64 vcc, exec, s[80:81]
	s_cbranch_vccnz .LBB0_1784
	s_mul_i32 s16, s77, 0xac00
	v_lshl_add_u64 v[102:103], v[118:119], 0, s[16:17]
	global_load_dwordx4 v[118:121], v[102:103], off offset:16
	global_load_dwordx4 v[126:129], v[102:103], off
	s_waitcnt vmcnt(0)
	s_branch .LBB0_1785

.LBB0_1785:
	s_waitcnt vmcnt(8)
	v_lshlrev_b32_e32 v106, 16, v112
	v_and_b32_e32 v107, 0xffff0000, v112
	v_lshlrev_b32_e32 v108, 16, v113
	v_and_b32_e32 v109, 0xffff0000, v113
	v_pk_fma_f32 v[112:113], v[126:127], v[14:15], v[6:7]
	v_lshlrev_b32_e32 v102, 16, v110
	v_and_b32_e32 v103, 0xffff0000, v110
	v_pk_fma_f32 v[112:113], v[122:123], v[22:23], v[112:113]
	v_lshlrev_b32_e32 v104, 16, v111
	v_pk_fma_f32 v[112:113], v[30:31], v[102:103], v[112:113]
	v_and_b32_e32 v105, 0xffff0000, v111
	v_pk_mul_f32 v[122:123], v[112:113], v[112:113]
	v_pk_fma_f32 v[110:111], v[128:129], v[16:17], v[8:9]
	v_fmamk_f32 v122, v122, 0xbdd2d3e7, v131
	v_mul_f32_e32 v122, v112, v122
	v_pk_fma_f32 v[110:111], v[124:125], v[24:25], v[110:111]
	v_exp_f32_e32 v124, v122
	v_fmamk_f32 v122, v123, 0xbdd2d3e7, v131
	v_pk_fma_f32 v[110:111], v[32:33], v[104:105], v[110:111]
	v_mul_f32_e32 v122, v113, v122
	v_exp_f32_e32 v125, v122
	v_pk_mul_f32 v[122:123], v[110:111], v[110:111]
	v_lshlrev_b32_e32 v126, 16, v98
	v_and_b32_e32 v127, 0xffff0000, v98
	v_fmamk_f32 v98, v122, 0xbdd2d3e7, v131
	v_mul_f32_e32 v98, v110, v98
	v_fmamk_f32 v122, v123, 0xbdd2d3e7, v131
	v_exp_f32_e32 v98, v98
	v_mul_f32_e32 v122, v111, v122
	v_exp_f32_e32 v123, v122
	v_pk_fma_f32 v[118:119], v[118:119], v[10:11], v[2:3]
	v_add_f32_e32 v98, 1.0, v98
	v_rcp_f32_e32 v122, v98
	v_add_f32_e32 v98, 1.0, v123
	v_rcp_f32_e32 v123, v98
	v_lshlrev_b32_e32 v98, 16, v99
	v_and_b32_e32 v99, 0xffff0000, v99
	v_pk_mul_f32 v[98:99], v[110:111], v[98:99]
	v_pk_fma_f32 v[114:115], v[114:115], v[18:19], v[118:119]
	v_pk_mul_f32 v[110:111], v[122:123], v[98:99]
	v_pk_fma_f32 v[98:99], v[120:121], v[12:13], v[4:5]
	v_pk_fma_f32 v[114:115], v[26:27], v[106:107], v[114:115]
	v_pk_fma_f32 v[98:99], v[116:117], v[20:21], v[98:99]
	v_pk_mul_f32 v[116:117], v[114:115], v[114:115]
	v_pk_fma_f32 v[98:99], v[28:29], v[108:109], v[98:99]
	v_fmamk_f32 v116, v116, 0xbdd2d3e7, v131
	v_mul_f32_e32 v116, v114, v116
	v_exp_f32_e32 v118, v116
	v_fmamk_f32 v116, v117, 0xbdd2d3e7, v131
	v_mul_f32_e32 v116, v115, v116
	v_exp_f32_e32 v119, v116
	v_pk_mul_f32 v[116:117], v[98:99], v[98:99]
	v_lshlrev_b32_e32 v120, 16, v100
	v_and_b32_e32 v121, 0xffff0000, v100
	v_fmamk_f32 v100, v116, 0xbdd2d3e7, v131
	v_mul_f32_e32 v100, v98, v100
	v_fmamk_f32 v116, v117, 0xbdd2d3e7, v131
	v_exp_f32_e32 v100, v100
	v_mul_f32_e32 v116, v99, v116
	v_exp_f32_e32 v117, v116
	v_add_f32_e32 v124, 1.0, v124
	v_add_f32_e32 v100, 1.0, v100
	v_add_f32_e32 v125, 1.0, v125
	v_add_f32_e32 v118, 1.0, v118
	v_add_f32_e32 v119, 1.0, v119
	v_rcp_f32_e32 v116, v100
	v_add_f32_e32 v100, 1.0, v117
	v_rcp_f32_e32 v124, v124
	v_rcp_f32_e32 v125, v125
	v_rcp_f32_e32 v118, v118
	v_rcp_f32_e32 v119, v119
	v_rcp_f32_e32 v117, v100
	v_lshlrev_b32_e32 v100, 16, v101
	v_and_b32_e32 v101, 0xffff0000, v101
	v_pk_mul_f32 v[112:113], v[112:113], v[126:127]
	v_pk_mul_f32 v[114:115], v[114:115], v[120:121]
	v_pk_mul_f32 v[98:99], v[98:99], v[100:101]
	s_and_b64 s[4:5], s[72:73], exec
	v_pk_mul_f32 v[112:113], v[124:125], v[112:113]
	v_pk_mul_f32 v[114:115], v[118:119], v[114:115]
	v_pk_mul_f32 v[116:117], v[116:117], v[98:99]
	s_cselect_b32 s4, 0x7fe, 6
	v_cvt_pk_bf16_f32 v98, v112, v113
	v_cvt_pk_bf16_f32 v99, v110, v111
	v_cvt_pk_bf16_f32 v100, v114, v115
	v_cvt_pk_bf16_f32 v101, v116, v117
	s_cmp_lt_u32 s77, s4
	global_store_dwordx4 v[142:143], v[98:101], off
	s_cbranch_scc1 .LBB0_1787
	s_lshl_b32 s5, s78, 1
	s_and_b64 s[72:73], s[72:73], exec
	s_cselect_b32 s16, s43, 0x1dda7c00
	s_add_u32 s16, s28, s16
	s_addc_u32 s36, s29, 0
	s_sub_i32 s4, s77, s4
	s_add_i32 s4, s5, s4
	s_mul_hi_i32 s5, s4, 0xac00
	s_mul_i32 s4, s4, 0xac00
	s_add_u32 s4, s16, s4
	s_addc_u32 s5, s36, s5
	v_lshl_add_u64 v[98:99], v[132:133], 2, s[4:5]
	global_store_dwordx4 v[98:99], v[102:105], off
	global_store_dwordx4 v[98:99], v[106:109], off offset:16
.LBB0_1787:
	s_add_i32 s77, s76, 1
	s_cmp_ge_i32 s77, s38
	s_cbranch_scc1 .LBB0_1790
	s_add_i32 s4, s76, 0xffffe001
	s_lshr_b32 s16, s4, 3
	s_ashr_i32 s36, s77, 11
	s_cmpk_lt_i32 s76, 0x1fff
	s_cselect_b64 s[72:73], -1, 0
	s_and_b64 s[4:5], s[72:73], exec
	s_load_dwordx2 s[4:5], s[0:1], 0x28
	s_cselect_b32 s37, 0x7ff, 7
	s_cselect_b32 s79, s36, s16
	s_and_b32 s78, s37, s77
	s_mul_i32 s36, s79, 0x15800
	s_mul_hi_i32 s16, s79, 0x15800
	s_waitcnt lgkmcnt(0)
	s_add_u32 s4, s4, s36
	s_addc_u32 s5, s5, s16
	s_cmp_lg_u32 s78, 0
	v_lshl_add_u64 v[98:99], v[132:133], 2, s[4:5]
	s_cselect_b64 s[4:5], -1, 0
	s_or_b64 s[80:81], s[4:5], s[72:73]
	s_and_b64 vcc, exec, s[80:81]
	s_cbranch_vccnz .LBB0_1793
	v_add_co_u32_e32 v110, vcc, 0xa000, v98
	v_lshl_add_u64 v[100:101], v[98:99], 0, s[18:19]
	s_nop 0
	v_addc_co_u32_e32 v111, vcc, 0, v99, vcc
	global_load_dwordx4 v[114:117], v[110:111], off offset:3072
	s_nop 0
	global_load_dwordx4 v[110:113], v[100:101], off offset:16
	s_waitcnt vmcnt(0)
	s_branch .LBB0_1794

.LBB0_1794:
	s_cmp_gt_u32 s78, 1
	s_cselect_b64 s[4:5], -1, 0
	s_or_b64 s[80:81], s[4:5], s[72:73]
	s_and_b64 vcc, exec, s[80:81]
	s_cbranch_vccnz .LBB0_1796
	s_mul_i32 s16, s78, 0xac00
	v_lshl_add_u64 v[74:75], v[98:99], 0, s[16:17]
	global_load_dwordx4 v[78:81], v[74:75], off offset:16
	s_nop 0
	global_load_dwordx4 v[74:77], v[74:75], off
	s_waitcnt vmcnt(0)
	s_branch .LBB0_1797

.LBB0_1797:
	v_pk_fma_f32 v[74:75], v[74:75], v[14:15], v[6:7]
	v_lshlrev_b32_e32 v98, 16, v94
	v_and_b32_e32 v99, 0xffff0000, v94
	v_pk_fma_f32 v[74:75], v[114:115], v[22:23], v[74:75]
	v_pk_fma_f32 v[76:77], v[76:77], v[16:17], v[8:9]
	v_pk_fma_f32 v[74:75], v[30:31], v[98:99], v[74:75]
	v_lshlrev_b32_e32 v100, 16, v95
	v_pk_mul_f32 v[114:115], v[74:75], v[74:75]
	v_and_b32_e32 v101, 0xffff0000, v95
	v_fmamk_f32 v114, v114, 0xbdd2d3e7, v131
	v_mul_f32_e32 v114, v74, v114
	v_pk_fma_f32 v[76:77], v[116:117], v[24:25], v[76:77]
	v_exp_f32_e32 v116, v114
	v_fmamk_f32 v114, v115, 0xbdd2d3e7, v131
	v_pk_fma_f32 v[76:77], v[32:33], v[100:101], v[76:77]
	v_mul_f32_e32 v114, v75, v114
	v_exp_f32_e32 v117, v114
	v_pk_mul_f32 v[114:115], v[76:77], v[76:77]
	v_lshlrev_b32_e32 v118, 16, v90
	v_and_b32_e32 v119, 0xffff0000, v90
	v_fmamk_f32 v90, v114, 0xbdd2d3e7, v131
	v_mul_f32_e32 v90, v76, v90
	v_fmamk_f32 v114, v115, 0xbdd2d3e7, v131
	v_exp_f32_e32 v90, v90
	v_mul_f32_e32 v114, v77, v114
	v_exp_f32_e32 v115, v114
	v_pk_fma_f32 v[78:79], v[78:79], v[10:11], v[2:3]
	v_add_f32_e32 v90, 1.0, v90
	v_lshlrev_b32_e32 v94, 16, v96
	v_and_b32_e32 v95, 0xffff0000, v96
	v_rcp_f32_e32 v114, v90
	v_add_f32_e32 v90, 1.0, v115
	v_pk_fma_f32 v[78:79], v[110:111], v[18:19], v[78:79]
	v_rcp_f32_e32 v115, v90
	v_lshlrev_b32_e32 v90, 16, v91
	v_and_b32_e32 v91, 0xffff0000, v91
	v_pk_fma_f32 v[78:79], v[26:27], v[94:95], v[78:79]
	v_pk_mul_f32 v[76:77], v[76:77], v[90:91]
	v_pk_mul_f32 v[90:91], v[78:79], v[78:79]
	v_pk_fma_f32 v[80:81], v[80:81], v[12:13], v[4:5]
	v_fmamk_f32 v90, v90, 0xbdd2d3e7, v131
	v_mul_f32_e32 v90, v78, v90
	v_lshlrev_b32_e32 v96, 16, v97
	v_and_b32_e32 v97, 0xffff0000, v97
	v_pk_fma_f32 v[80:81], v[112:113], v[20:21], v[80:81]
	v_exp_f32_e32 v110, v90
	v_fmamk_f32 v90, v91, 0xbdd2d3e7, v131
	v_pk_fma_f32 v[80:81], v[28:29], v[96:97], v[80:81]
	v_mul_f32_e32 v90, v79, v90
	v_exp_f32_e32 v111, v90
	v_pk_mul_f32 v[90:91], v[80:81], v[80:81]
	v_add_f32_e32 v116, 1.0, v116
	v_fmamk_f32 v90, v90, 0xbdd2d3e7, v131
	v_fmamk_f32 v91, v91, 0xbdd2d3e7, v131
	v_mul_f32_e32 v90, v80, v90
	v_mul_f32_e32 v91, v81, v91
	v_exp_f32_e32 v90, v90
	v_exp_f32_e32 v91, v91
	v_add_f32_e32 v117, 1.0, v117
	v_add_f32_e32 v110, 1.0, v110
	v_add_f32_e32 v111, 1.0, v111
	v_rcp_f32_e32 v116, v116
	v_rcp_f32_e32 v117, v117
	v_rcp_f32_e32 v110, v110
	v_rcp_f32_e32 v111, v111
	v_add_f32_e32 v90, 1.0, v90
	v_add_f32_e32 v91, 1.0, v91
	v_lshlrev_b32_e32 v112, 16, v92
	v_and_b32_e32 v113, 0xffff0000, v92
	v_rcp_f32_e32 v90, v90
	v_rcp_f32_e32 v91, v91
	v_pk_mul_f32 v[74:75], v[74:75], v[118:119]
	v_pk_mul_f32 v[78:79], v[78:79], v[112:113]
	v_pk_mul_f32 v[74:75], v[116:117], v[74:75]
	v_pk_mul_f32 v[76:77], v[114:115], v[76:77]
	v_pk_mul_f32 v[78:79], v[110:111], v[78:79]
	v_lshlrev_b32_e32 v92, 16, v93
	v_and_b32_e32 v93, 0xffff0000, v93
	v_pk_mul_f32 v[80:81], v[80:81], v[92:93]
	v_cvt_pk_bf16_f32 v74, v74, v75
	v_cvt_pk_bf16_f32 v75, v76, v77
	v_cvt_pk_bf16_f32 v76, v78, v79
	v_mad_i64_i32 v[78:79], s[4:5], s77, v146, v[138:139]
	s_and_b64 s[4:5], s[72:73], exec
	v_pk_mul_f32 v[80:81], v[90:91], v[80:81]
	s_cselect_b32 s4, 0x7fe, 6
	v_cvt_pk_bf16_f32 v77, v80, v81
	s_cmp_lt_u32 s78, s4
	global_store_dwordx4 v[78:79], v[74:77], off
	s_cbranch_scc1 .LBB0_1799
	s_lshl_b32 s5, s79, 1
	s_and_b64 s[72:73], s[72:73], exec
	s_cselect_b32 s16, s43, 0x1dda7c00
	s_add_u32 s16, s28, s16
	s_addc_u32 s36, s29, 0
	s_sub_i32 s4, s78, s4
	s_add_i32 s4, s5, s4
	s_mul_hi_i32 s5, s4, 0xac00
	s_mul_i32 s4, s4, 0xac00
	s_add_u32 s4, s16, s4
	s_addc_u32 s5, s36, s5
	v_lshl_add_u64 v[74:75], v[132:133], 2, s[4:5]
	global_store_dwordx4 v[74:75], v[98:101], off
	global_store_dwordx4 v[74:75], v[94:97], off offset:16

.LBB0_1800:
	s_add_i32 s4, s76, 0xffffe002
	s_lshr_b32 s16, s4, 3
	s_ashr_i32 s36, s77, 11
	s_cmpk_lt_i32 s76, 0x1ffe
	s_cselect_b64 s[72:73], -1, 0
	s_and_b64 s[4:5], s[72:73], exec
	s_load_dwordx2 s[4:5], s[0:1], 0x28
	s_cselect_b32 s37, 0x7ff, 7
	s_cselect_b32 s79, s36, s16
	s_and_b32 s78, s37, s77
	s_mul_i32 s36, s79, 0x15800
	s_mul_hi_i32 s16, s79, 0x15800
	s_waitcnt lgkmcnt(0)
	s_add_u32 s4, s4, s36
	s_addc_u32 s5, s5, s16
	s_cmp_lg_u32 s78, 0
	v_lshl_add_u64 v[90:91], v[132:133], 2, s[4:5]
	s_cselect_b64 s[4:5], -1, 0
	s_or_b64 s[80:81], s[4:5], s[72:73]
	s_and_b64 vcc, exec, s[80:81]
	s_cbranch_vccnz .LBB0_1802
	v_add_co_u32_e32 v102, vcc, 0xa000, v90
	v_lshl_add_u64 v[92:93], v[90:91], 0, s[18:19]
	s_nop 0
	v_addc_co_u32_e32 v103, vcc, 0, v91, vcc
	global_load_dwordx4 v[106:109], v[102:103], off offset:3072
	s_nop 0
	global_load_dwordx4 v[102:105], v[92:93], off offset:16
	s_waitcnt vmcnt(0)
	s_branch .LBB0_1803

.LBB0_1803:
	s_cmp_gt_u32 s78, 1
	s_cselect_b64 s[4:5], -1, 0
	s_or_b64 s[80:81], s[4:5], s[72:73]
	s_and_b64 vcc, exec, s[80:81]
	s_cbranch_vccnz .LBB0_1805
	s_mul_i32 s16, s78, 0xac00
	v_lshl_add_u64 v[74:75], v[90:91], 0, s[16:17]
	global_load_dwordx4 v[78:81], v[74:75], off offset:16
	s_nop 0
	global_load_dwordx4 v[74:77], v[74:75], off
	s_waitcnt vmcnt(0)
	s_branch .LBB0_1806

.LBB0_1806:
	v_pk_fma_f32 v[74:75], v[74:75], v[14:15], v[6:7]
	v_lshlrev_b32_e32 v90, 16, v86
	v_and_b32_e32 v91, 0xffff0000, v86
	v_pk_fma_f32 v[74:75], v[106:107], v[22:23], v[74:75]
	v_pk_fma_f32 v[76:77], v[76:77], v[16:17], v[8:9]
	v_pk_fma_f32 v[74:75], v[30:31], v[90:91], v[74:75]
	v_lshlrev_b32_e32 v92, 16, v87
	v_pk_mul_f32 v[106:107], v[74:75], v[74:75]
	v_and_b32_e32 v93, 0xffff0000, v87
	v_fmamk_f32 v106, v106, 0xbdd2d3e7, v131
	v_mul_f32_e32 v106, v74, v106
	v_pk_fma_f32 v[76:77], v[108:109], v[24:25], v[76:77]
	v_exp_f32_e32 v108, v106
	v_fmamk_f32 v106, v107, 0xbdd2d3e7, v131
	v_pk_fma_f32 v[76:77], v[32:33], v[92:93], v[76:77]
	v_mul_f32_e32 v106, v75, v106
	v_exp_f32_e32 v109, v106
	v_pk_mul_f32 v[106:107], v[76:77], v[76:77]
	v_lshlrev_b32_e32 v110, 16, v82
	v_and_b32_e32 v111, 0xffff0000, v82
	v_fmamk_f32 v82, v106, 0xbdd2d3e7, v131
	v_mul_f32_e32 v82, v76, v82
	v_fmamk_f32 v106, v107, 0xbdd2d3e7, v131
	v_exp_f32_e32 v82, v82
	v_mul_f32_e32 v106, v77, v106
	v_exp_f32_e32 v107, v106
	v_pk_fma_f32 v[78:79], v[78:79], v[10:11], v[2:3]
	v_add_f32_e32 v82, 1.0, v82
	v_lshlrev_b32_e32 v86, 16, v88
	v_and_b32_e32 v87, 0xffff0000, v88
	v_rcp_f32_e32 v106, v82
	v_add_f32_e32 v82, 1.0, v107
	v_pk_fma_f32 v[78:79], v[102:103], v[18:19], v[78:79]
	v_rcp_f32_e32 v107, v82
	v_lshlrev_b32_e32 v82, 16, v83
	v_and_b32_e32 v83, 0xffff0000, v83
	v_pk_fma_f32 v[78:79], v[26:27], v[86:87], v[78:79]
	v_pk_mul_f32 v[76:77], v[76:77], v[82:83]
	v_pk_mul_f32 v[82:83], v[78:79], v[78:79]
	v_pk_fma_f32 v[80:81], v[80:81], v[12:13], v[4:5]
	v_fmamk_f32 v82, v82, 0xbdd2d3e7, v131
	v_mul_f32_e32 v82, v78, v82
	v_lshlrev_b32_e32 v88, 16, v89
	v_and_b32_e32 v89, 0xffff0000, v89
	v_pk_fma_f32 v[80:81], v[104:105], v[20:21], v[80:81]
	v_exp_f32_e32 v102, v82
	v_fmamk_f32 v82, v83, 0xbdd2d3e7, v131
	v_pk_fma_f32 v[80:81], v[28:29], v[88:89], v[80:81]
	v_mul_f32_e32 v82, v79, v82
	v_exp_f32_e32 v103, v82
	v_pk_mul_f32 v[82:83], v[80:81], v[80:81]
	v_add_f32_e32 v108, 1.0, v108
	v_fmamk_f32 v82, v82, 0xbdd2d3e7, v131
	v_fmamk_f32 v83, v83, 0xbdd2d3e7, v131
	v_mul_f32_e32 v82, v80, v82
	v_mul_f32_e32 v83, v81, v83
	v_exp_f32_e32 v82, v82
	v_exp_f32_e32 v83, v83
	v_add_f32_e32 v109, 1.0, v109
	v_add_f32_e32 v102, 1.0, v102
	v_add_f32_e32 v103, 1.0, v103
	v_rcp_f32_e32 v108, v108
	v_rcp_f32_e32 v109, v109
	v_rcp_f32_e32 v102, v102
	v_rcp_f32_e32 v103, v103
	v_add_f32_e32 v82, 1.0, v82
	v_add_f32_e32 v83, 1.0, v83
	v_lshlrev_b32_e32 v104, 16, v84
	v_and_b32_e32 v105, 0xffff0000, v84
	v_rcp_f32_e32 v82, v82
	v_rcp_f32_e32 v83, v83
	v_pk_mul_f32 v[74:75], v[74:75], v[110:111]
	v_pk_mul_f32 v[78:79], v[78:79], v[104:105]
	v_pk_mul_f32 v[74:75], v[108:109], v[74:75]
	v_pk_mul_f32 v[76:77], v[106:107], v[76:77]
	v_pk_mul_f32 v[78:79], v[102:103], v[78:79]
	v_lshlrev_b32_e32 v84, 16, v85
	v_and_b32_e32 v85, 0xffff0000, v85
	v_pk_mul_f32 v[80:81], v[80:81], v[84:85]
	v_cvt_pk_bf16_f32 v74, v74, v75
	v_cvt_pk_bf16_f32 v75, v76, v77
	v_cvt_pk_bf16_f32 v76, v78, v79
	v_mad_i64_i32 v[78:79], s[4:5], s77, v146, v[138:139]
	s_and_b64 s[4:5], s[72:73], exec
	v_pk_mul_f32 v[80:81], v[82:83], v[80:81]
	s_cselect_b32 s4, 0x7fe, 6
	v_cvt_pk_bf16_f32 v77, v80, v81
	s_cmp_lt_u32 s78, s4
	global_store_dwordx4 v[78:79], v[74:77], off
	s_cbranch_scc1 .LBB0_1808
	s_lshl_b32 s5, s79, 1
	s_and_b64 s[72:73], s[72:73], exec
	s_cselect_b32 s16, s43, 0x1dda7c00
	s_add_u32 s16, s28, s16
	s_addc_u32 s36, s29, 0
	s_sub_i32 s4, s78, s4
	s_add_i32 s4, s5, s4
	s_mul_hi_i32 s5, s4, 0xac00
	s_mul_i32 s4, s4, 0xac00
	s_add_u32 s4, s16, s4
	s_addc_u32 s5, s36, s5
	v_lshl_add_u64 v[74:75], v[132:133], 2, s[4:5]
	global_store_dwordx4 v[74:75], v[90:93], off
	global_store_dwordx4 v[74:75], v[86:89], off offset:16

.LBB0_1809:
	s_add_i32 s4, s76, 0xffffe003
	s_lshr_b32 s16, s4, 3
	s_ashr_i32 s36, s77, 11
	s_cmpk_lt_i32 s76, 0x1ffd
	s_cselect_b64 s[72:73], -1, 0
	s_and_b64 s[4:5], s[72:73], exec
	s_load_dwordx2 s[4:5], s[0:1], 0x28
	s_cselect_b32 s37, 0x7ff, 7
	s_cselect_b32 s78, s36, s16
	s_and_b32 s76, s37, s77
	s_mul_i32 s36, s78, 0x15800
	s_mul_hi_i32 s16, s78, 0x15800
	s_waitcnt lgkmcnt(0)
	s_add_u32 s4, s4, s36
	s_addc_u32 s5, s5, s16
	s_cmp_lg_u32 s76, 0
	v_lshl_add_u64 v[94:95], v[132:133], 2, s[4:5]
	s_cselect_b64 s[4:5], -1, 0
	s_or_b64 s[80:81], s[4:5], s[72:73]
	s_and_b64 vcc, exec, s[80:81]
	s_cbranch_vccnz .LBB0_1811
	v_add_co_u32_e32 v84, vcc, 0xa000, v94
	v_lshl_add_u64 v[82:83], v[94:95], 0, s[18:19]
	s_nop 0
	v_addc_co_u32_e32 v85, vcc, 0, v95, vcc
	global_load_dwordx4 v[98:101], v[84:85], off offset:3072
	s_nop 0
	global_load_dwordx4 v[82:85], v[82:83], off offset:16
	s_waitcnt vmcnt(0)
	s_branch .LBB0_1812

.LBB0_1812:
	s_cmp_gt_u32 s76, 1
	s_cselect_b64 s[4:5], -1, 0
	s_or_b64 s[80:81], s[4:5], s[72:73]
	s_and_b64 vcc, exec, s[80:81]
	s_cbranch_vccnz .LBB0_1814
	s_mul_i32 s16, s76, 0xac00
	v_lshl_add_u64 v[74:75], v[94:95], 0, s[16:17]
	global_load_dwordx4 v[94:97], v[74:75], off offset:16
	global_load_dwordx4 v[102:105], v[74:75], off
	s_waitcnt vmcnt(0)
	s_branch .LBB0_1815

.LBB0_1815:
	v_lshlrev_b32_e32 v78, 16, v72
	v_and_b32_e32 v79, 0xffff0000, v72
	v_lshlrev_b32_e32 v80, 16, v73
	v_and_b32_e32 v81, 0xffff0000, v73
	v_pk_fma_f32 v[72:73], v[102:103], v[14:15], v[6:7]
	v_lshlrev_b32_e32 v74, 16, v70
	v_and_b32_e32 v75, 0xffff0000, v70
	v_pk_fma_f32 v[72:73], v[98:99], v[22:23], v[72:73]
	v_lshlrev_b32_e32 v76, 16, v71
	v_pk_fma_f32 v[72:73], v[30:31], v[74:75], v[72:73]
	v_and_b32_e32 v77, 0xffff0000, v71
	v_pk_mul_f32 v[98:99], v[72:73], v[72:73]
	v_pk_fma_f32 v[70:71], v[104:105], v[16:17], v[8:9]
	v_fmamk_f32 v98, v98, 0xbdd2d3e7, v131
	v_mul_f32_e32 v98, v72, v98
	v_pk_fma_f32 v[70:71], v[100:101], v[24:25], v[70:71]
	v_exp_f32_e32 v100, v98
	v_fmamk_f32 v98, v99, 0xbdd2d3e7, v131
	v_pk_fma_f32 v[70:71], v[32:33], v[76:77], v[70:71]
	v_mul_f32_e32 v98, v73, v98
	v_exp_f32_e32 v101, v98
	v_pk_mul_f32 v[98:99], v[70:71], v[70:71]
	v_lshlrev_b32_e32 v102, 16, v34
	v_and_b32_e32 v103, 0xffff0000, v34
	v_fmamk_f32 v34, v98, 0xbdd2d3e7, v131
	v_mul_f32_e32 v34, v70, v34
	v_fmamk_f32 v98, v99, 0xbdd2d3e7, v131
	v_exp_f32_e32 v34, v34
	v_mul_f32_e32 v98, v71, v98
	v_exp_f32_e32 v99, v98
	v_pk_fma_f32 v[94:95], v[94:95], v[10:11], v[2:3]
	v_add_f32_e32 v34, 1.0, v34
	v_rcp_f32_e32 v98, v34
	v_add_f32_e32 v34, 1.0, v99
	v_rcp_f32_e32 v99, v34
	v_lshlrev_b32_e32 v34, 16, v35
	v_and_b32_e32 v35, 0xffff0000, v35
	v_pk_mul_f32 v[34:35], v[70:71], v[34:35]
	v_pk_fma_f32 v[82:83], v[82:83], v[18:19], v[94:95]
	v_pk_mul_f32 v[70:71], v[98:99], v[34:35]
	v_pk_fma_f32 v[34:35], v[96:97], v[12:13], v[4:5]
	v_pk_fma_f32 v[82:83], v[26:27], v[78:79], v[82:83]
	v_pk_fma_f32 v[34:35], v[84:85], v[20:21], v[34:35]
	v_pk_mul_f32 v[84:85], v[82:83], v[82:83]
	v_pk_fma_f32 v[34:35], v[28:29], v[80:81], v[34:35]
	v_fmamk_f32 v84, v84, 0xbdd2d3e7, v131
	v_mul_f32_e32 v84, v82, v84
	v_exp_f32_e32 v94, v84
	v_fmamk_f32 v84, v85, 0xbdd2d3e7, v131
	v_mul_f32_e32 v84, v83, v84
	v_exp_f32_e32 v95, v84
	v_pk_mul_f32 v[84:85], v[34:35], v[34:35]
	v_lshlrev_b32_e32 v96, 16, v36
	v_and_b32_e32 v97, 0xffff0000, v36
	v_fmamk_f32 v36, v84, 0xbdd2d3e7, v131
	v_mul_f32_e32 v36, v34, v36
	v_fmamk_f32 v84, v85, 0xbdd2d3e7, v131
	v_exp_f32_e32 v36, v36
	v_mul_f32_e32 v84, v35, v84
	v_exp_f32_e32 v85, v84
	v_add_f32_e32 v100, 1.0, v100
	v_add_f32_e32 v36, 1.0, v36
	v_rcp_f32_e32 v84, v36
	v_add_f32_e32 v36, 1.0, v85
	v_add_f32_e32 v101, 1.0, v101
	v_add_f32_e32 v94, 1.0, v94
	v_add_f32_e32 v95, 1.0, v95
	v_rcp_f32_e32 v85, v36
	v_rcp_f32_e32 v100, v100
	v_rcp_f32_e32 v101, v101
	v_rcp_f32_e32 v94, v94
	v_rcp_f32_e32 v95, v95
	v_lshlrev_b32_e32 v36, 16, v37
	v_and_b32_e32 v37, 0xffff0000, v37
	v_pk_mul_f32 v[34:35], v[34:35], v[36:37]
	v_pk_mul_f32 v[72:73], v[72:73], v[102:103]
	v_pk_mul_f32 v[82:83], v[82:83], v[96:97]
	v_pk_mul_f32 v[84:85], v[84:85], v[34:35]
	v_cvt_pk_bf16_f32 v35, v70, v71
	v_mad_i64_i32 v[70:71], s[4:5], s77, v146, v[138:139]
	s_and_b64 s[4:5], s[72:73], exec
	v_pk_mul_f32 v[72:73], v[100:101], v[72:73]
	v_pk_mul_f32 v[82:83], v[94:95], v[82:83]
	s_cselect_b32 s4, 0x7fe, 6
	v_cvt_pk_bf16_f32 v34, v72, v73
	v_cvt_pk_bf16_f32 v36, v82, v83
	v_cvt_pk_bf16_f32 v37, v84, v85
	s_cmp_lt_u32 s76, s4
	global_store_dwordx4 v[70:71], v[34:37], off
	s_cbranch_scc1 .LBB0_1777
	s_lshl_b32 s5, s78, 1
	s_and_b64 s[72:73], s[72:73], exec
	s_cselect_b32 s16, s43, 0x1dda7c00
	s_add_u32 s16, s28, s16
	s_addc_u32 s36, s29, 0
	s_sub_i32 s4, s76, s4
	s_add_i32 s4, s5, s4
	s_mul_hi_i32 s5, s4, 0xac00
	s_mul_i32 s4, s4, 0xac00
	s_add_u32 s4, s16, s4
	s_addc_u32 s5, s36, s5
	v_lshl_add_u64 v[34:35], v[132:133], 2, s[4:5]
	global_store_dwordx4 v[34:35], v[74:77], off
	global_store_dwordx4 v[34:35], v[78:81], off offset:16
	s_branch .LBB0_1777
